# forget-logit tile epilogue of the projection GEMM: log_sigmoid hand-written in f32 (hi/lo-split exp2 + ldexp, log1p via log(u)*e/(u-1) with refined quotient and hi/lo ln2) replacing ~7000 library inst
# speedup vs baseline: 1.0100x; 1.0100x over previous
; __device__ __forceinline__ float log_sigmoid_(float x) { return fminf(x, 0.f) - log1pf(expf(-fabsf(x))); }
;     __device__ __forceinline__ void operator()(const f32x4 (&acc)[2][2][4][2], const pg8::Unit& u, int wr, int wc, int fr, int fq) const {
;     ...
;         } else {
;             if (wc == 0 && fq == 0) {
;                 const f32x4 b0 = *(const f32x4*)bf, b1 = *(const f32x4*)(bf + 4);
; #pragma unroll
;                 for (int ai = 0; ai < 2; ++ai)
; #pragma unroll
;                     for (int m = 0; m < 4; ++m) { const int r = row0 + ai * 128 + m * 16; const f32x4 v0 = acc[ai][0][m][0] + b0, v1 = acc[ai][0][m][1] + b1;
;                         f32x4 l0, l1;
; #pragma unroll
;                         for (int j = 0; j < 4; ++j) { l0[j] = log_sigmoid_(v0[j]); l1[j] = log_sigmoid_(v1[j]); }
;                         float* dst = out + (smp ? O_FLS + (size_t)(r - MP) * 8 : O_FLP + (size_t)r * 8);
;                         *(f32x4*)dst = l0; *(f32x4*)(dst + 4) = l1; }
.LBB0_486:
	s_lshl_b32 s53, s0, 8
	s_add_i32 s53, s53, s66
	v_or_b32_e32 v176, s53, v161
	s_cmp_gt_i32 s60, 1
	s_mov_b64 s[2:3], -1
	s_mov_b32 s74, 0x800000
	s_cbranch_scc0 .LBB0_547
	s_cmpk_gt_i32 s0, 0xff
	s_cselect_b64 s[46:47], -1, 0
	s_cmp_gt_u32 s60, 5
	s_mov_b64 s[0:1], -1
	s_cbranch_scc0 .LBB0_543
	s_cmp_gt_u32 s60, 12
	s_cbranch_scc0 .LBB0_492
	s_and_saveexec_b64 s[0:1], s[40:41]
	s_cbranch_execz .LBB0_491
	s_load_dwordx2 s[2:3], s[38:39], 0x58
	s_mov_b32 s5, 0xb2a5705f
	s_mov_b32 s16, 0x3f317218
	s_mov_b32 s17, 0xb102e308
	s_waitcnt lgkmcnt(0)
	global_load_dwordx4 v[134:137], v1, s[2:3]
	global_load_dwordx4 v[130:133], v1, s[2:3] offset:16
	s_waitcnt vmcnt(0)
	s_and_b64 s[2:3], s[46:47], exec
	s_mov_b32 s2, 0x20a38000
	s_cselect_b32 s12, s2, 0x20200000
	s_cselect_b32 s2, 0xffff0000, 0
	v_add_u32_e32 v146, s2, v176
	v_ashrrev_i32_e32 v147, 31, v146
	v_lshlrev_b64 v[146:147], 5, v[146:147]
	v_lshl_add_u64 v[146:147], s[6:7], 0, v[146:147]
	v_lshl_add_u64 v[146:147], v[146:147], 0, s[12:13]
	s_mov_b32 s2, 0x1000
	s_mov_b32 s3, 0
	v_lshl_add_u64 v[214:215], v[146:147], 0, s[2:3]
	v_add_f32_e32 v177, v126, v134
	v_add_f32_e32 v178, v127, v135
	v_add_f32_e32 v179, v128, v136
	v_add_f32_e32 v182, v129, v137
	v_mul_f32_e64 v187, |v177|, s76
	v_mul_f32_e64 v188, |v178|, s76
	v_mul_f32_e64 v189, |v179|, s76
	v_mul_f32_e64 v190, |v182|, s76
	v_fma_f32 v191, |v177|, s76, -v187
	v_fma_f32 v0, |v178|, s76, -v188
	v_fma_f32 v216, |v179|, s76, -v189
	v_fma_f32 v217, |v182|, s76, -v190
	v_rndne_f32_e32 v206, v187
	v_rndne_f32_e32 v207, v188
	v_rndne_f32_e32 v208, v189
	v_rndne_f32_e32 v209, v190
	v_fma_f32 v191, |v177|, s5, v191
	v_fma_f32 v0, |v178|, s5, v0
	v_fma_f32 v216, |v179|, s5, v216
	v_fma_f32 v217, |v182|, s5, v217
	v_sub_f32_e32 v187, v187, v206
	v_sub_f32_e32 v188, v188, v207
	v_sub_f32_e32 v189, v189, v208
	v_sub_f32_e32 v190, v190, v209
	v_add_f32_e32 v187, v187, v191
	v_add_f32_e32 v188, v188, v0
	v_add_f32_e32 v189, v189, v216
	v_add_f32_e32 v190, v190, v217
	v_cvt_i32_f32_e32 v206, v206
	v_cvt_i32_f32_e32 v207, v207
	v_cvt_i32_f32_e32 v208, v208
	v_cvt_i32_f32_e32 v209, v209
	v_exp_f32_e32 v183, v187
	v_exp_f32_e32 v184, v188
	v_exp_f32_e32 v185, v189
	v_exp_f32_e32 v186, v190
	v_ldexp_f32 v183, v183, v206
	v_ldexp_f32 v184, v184, v207
	v_ldexp_f32 v185, v185, v208
	v_ldexp_f32 v186, v186, v209
	v_add_f32_e32 v187, 1.0, v183
	v_add_f32_e32 v188, 1.0, v184
	v_add_f32_e32 v189, 1.0, v185
	v_add_f32_e32 v190, 1.0, v186
	v_add_f32_e32 v191, -1.0, v187
	v_add_f32_e32 v0, -1.0, v188
	v_add_f32_e32 v216, -1.0, v189
	v_add_f32_e32 v217, -1.0, v190
	v_log_f32_e32 v187, v187
	v_log_f32_e32 v188, v188
	v_log_f32_e32 v189, v189
	v_log_f32_e32 v190, v190
	v_rcp_f32_e32 v206, v191
	v_rcp_f32_e32 v207, v0
	v_rcp_f32_e32 v208, v216
	v_rcp_f32_e32 v209, v217
	v_mul_f32_e32 v210, v183, v206
	v_mul_f32_e32 v211, v184, v207
	v_mul_f32_e32 v212, v185, v208
	v_mul_f32_e32 v213, v186, v209
	v_fma_f32 v138, -v210, v191, v183
	v_fma_f32 v139, -v211, v0, v184
	v_fma_f32 v140, -v212, v216, v185
	v_fma_f32 v141, -v213, v217, v186
	v_fma_f32 v210, v138, v206, v210
	v_fma_f32 v211, v139, v207, v211
	v_fma_f32 v212, v140, v208, v212
	v_fma_f32 v213, v141, v209, v213
	v_mul_f32_e32 v206, s16, v187
	v_mul_f32_e32 v207, s16, v188
	v_mul_f32_e32 v208, s16, v189
	v_mul_f32_e32 v209, s16, v190
	v_fma_f32 v138, v187, s16, -v206
	v_fma_f32 v139, v188, s16, -v207
	v_fma_f32 v140, v189, s16, -v208
	v_fma_f32 v141, v190, s16, -v209
	v_fma_f32 v138, v187, s17, v138
	v_fma_f32 v139, v188, s17, v139
	v_fma_f32 v140, v189, s17, v140
	v_fma_f32 v141, v190, s17, v141
	v_add_f32_e32 v206, v206, v138
	v_add_f32_e32 v207, v207, v139
	v_add_f32_e32 v208, v208, v140
	v_add_f32_e32 v209, v209, v141
	v_mul_f32_e32 v206, v206, v210
	v_mul_f32_e32 v207, v207, v211
	v_mul_f32_e32 v208, v208, v212
	v_mul_f32_e32 v209, v209, v213
	v_min_f32_e32 v187, 0, v177
	v_min_f32_e32 v188, 0, v178
	v_min_f32_e32 v189, 0, v179
	v_min_f32_e32 v190, 0, v182
	v_cmp_eq_f32_e32 vcc, 0, v191
	s_nop 1
	v_cndmask_b32_e32 v206, v206, v183, vcc
	v_cmp_eq_f32_e32 vcc, 0, v0
	s_nop 1
	v_cndmask_b32_e32 v207, v207, v184, vcc
	v_cmp_eq_f32_e32 vcc, 0, v216
	s_nop 1
	v_cndmask_b32_e32 v208, v208, v185, vcc
	v_cmp_eq_f32_e32 vcc, 0, v217
	s_nop 1
	v_cndmask_b32_e32 v209, v209, v186, vcc
	v_sub_f32_e32 v138, v187, v206
	v_sub_f32_e32 v139, v188, v207
	v_sub_f32_e32 v140, v189, v208
	v_sub_f32_e32 v141, v190, v209
	v_add_f32_e32 v177, v122, v130
	v_add_f32_e32 v178, v123, v131
	v_add_f32_e32 v179, v124, v132
	v_add_f32_e32 v182, v125, v133
	v_mul_f32_e64 v187, |v177|, s76
	v_mul_f32_e64 v188, |v178|, s76
	v_mul_f32_e64 v189, |v179|, s76
	v_mul_f32_e64 v190, |v182|, s76
	v_fma_f32 v191, |v177|, s76, -v187
	v_fma_f32 v0, |v178|, s76, -v188
	v_fma_f32 v216, |v179|, s76, -v189
	v_fma_f32 v217, |v182|, s76, -v190
	v_rndne_f32_e32 v206, v187
	v_rndne_f32_e32 v207, v188
	v_rndne_f32_e32 v208, v189
	v_rndne_f32_e32 v209, v190
	v_fma_f32 v191, |v177|, s5, v191
	v_fma_f32 v0, |v178|, s5, v0
	v_fma_f32 v216, |v179|, s5, v216
	v_fma_f32 v217, |v182|, s5, v217
	v_sub_f32_e32 v187, v187, v206
	v_sub_f32_e32 v188, v188, v207
	v_sub_f32_e32 v189, v189, v208
	v_sub_f32_e32 v190, v190, v209
	v_add_f32_e32 v187, v187, v191
	v_add_f32_e32 v188, v188, v0
	v_add_f32_e32 v189, v189, v216
	v_add_f32_e32 v190, v190, v217
	v_cvt_i32_f32_e32 v206, v206
	v_cvt_i32_f32_e32 v207, v207
	v_cvt_i32_f32_e32 v208, v208
	v_cvt_i32_f32_e32 v209, v209
	v_exp_f32_e32 v183, v187
	v_exp_f32_e32 v184, v188
	v_exp_f32_e32 v185, v189
	v_exp_f32_e32 v186, v190
	v_ldexp_f32 v183, v183, v206
	v_ldexp_f32 v184, v184, v207
	v_ldexp_f32 v185, v185, v208
; __device__ __forceinline__ float log_sigmoid_(float x) { return fminf(x, 0.f) - log1pf(expf(-fabsf(x))); }
;     __device__ __forceinline__ void operator()(const f32x4 (&acc)[2][2][4][2], const pg8::Unit& u, int wr, int wc, int fr, int fq) const {
;     ...
;                     for (int m = 0; m < 4; ++m) { const int r = row0 + ai * 128 + m * 16; const f32x4 v0 = acc[ai][0][m][0] + b0, v1 = acc[ai][0][m][1] + b1;
;                         f32x4 l0, l1;
; #pragma unroll
;                         for (int j = 0; j < 4; ++j) { l0[j] = log_sigmoid_(v0[j]); l1[j] = log_sigmoid_(v1[j]); }
;                         float* dst = out + (smp ? O_FLS + (size_t)(r - MP) * 8 : O_FLP + (size_t)r * 8);
;                         *(f32x4*)dst = l0; *(f32x4*)(dst + 4) = l1; }
	v_ldexp_f32 v186, v186, v209
	v_add_f32_e32 v187, 1.0, v183
	v_add_f32_e32 v188, 1.0, v184
	v_add_f32_e32 v189, 1.0, v185
	v_add_f32_e32 v190, 1.0, v186
	v_add_f32_e32 v191, -1.0, v187
	v_add_f32_e32 v0, -1.0, v188
	v_add_f32_e32 v216, -1.0, v189
	v_add_f32_e32 v217, -1.0, v190
	v_log_f32_e32 v187, v187
	v_log_f32_e32 v188, v188
	v_log_f32_e32 v189, v189
	v_log_f32_e32 v190, v190
	v_rcp_f32_e32 v206, v191
	v_rcp_f32_e32 v207, v0
	v_rcp_f32_e32 v208, v216
	v_rcp_f32_e32 v209, v217
	v_mul_f32_e32 v210, v183, v206
	v_mul_f32_e32 v211, v184, v207
	v_mul_f32_e32 v212, v185, v208
	v_mul_f32_e32 v213, v186, v209
	v_fma_f32 v142, -v210, v191, v183
	v_fma_f32 v143, -v211, v0, v184
	v_fma_f32 v144, -v212, v216, v185
	v_fma_f32 v145, -v213, v217, v186
	v_fma_f32 v210, v142, v206, v210
	v_fma_f32 v211, v143, v207, v211
	v_fma_f32 v212, v144, v208, v212
	v_fma_f32 v213, v145, v209, v213
	v_mul_f32_e32 v206, s16, v187
	v_mul_f32_e32 v207, s16, v188
	v_mul_f32_e32 v208, s16, v189
	v_mul_f32_e32 v209, s16, v190
	v_fma_f32 v142, v187, s16, -v206
	v_fma_f32 v143, v188, s16, -v207
	v_fma_f32 v144, v189, s16, -v208
	v_fma_f32 v145, v190, s16, -v209
	v_fma_f32 v142, v187, s17, v142
	v_fma_f32 v143, v188, s17, v143
	v_fma_f32 v144, v189, s17, v144
	v_fma_f32 v145, v190, s17, v145
	v_add_f32_e32 v206, v206, v142
	v_add_f32_e32 v207, v207, v143
	v_add_f32_e32 v208, v208, v144
	v_add_f32_e32 v209, v209, v145
	v_mul_f32_e32 v206, v206, v210
	v_mul_f32_e32 v207, v207, v211
	v_mul_f32_e32 v208, v208, v212
	v_mul_f32_e32 v209, v209, v213
	v_min_f32_e32 v187, 0, v177
	v_min_f32_e32 v188, 0, v178
	v_min_f32_e32 v189, 0, v179
	v_min_f32_e32 v190, 0, v182
	v_cmp_eq_f32_e32 vcc, 0, v191
	s_nop 1
	v_cndmask_b32_e32 v206, v206, v183, vcc
	v_cmp_eq_f32_e32 vcc, 0, v0
	s_nop 1
	v_cndmask_b32_e32 v207, v207, v184, vcc
	v_cmp_eq_f32_e32 vcc, 0, v216
	s_nop 1
	v_cndmask_b32_e32 v208, v208, v185, vcc
	v_cmp_eq_f32_e32 vcc, 0, v217
	s_nop 1
	v_cndmask_b32_e32 v209, v209, v186, vcc
	v_sub_f32_e32 v142, v187, v206
	v_sub_f32_e32 v143, v188, v207
	v_sub_f32_e32 v144, v189, v208
	v_sub_f32_e32 v145, v190, v209
	global_store_dwordx4 v[146:147], v[138:141], off
	global_store_dwordx4 v[146:147], v[142:145], off offset:16
	s_nop 1
	v_add_f32_e32 v177, v110, v134
	v_add_f32_e32 v178, v111, v135
	v_add_f32_e32 v179, v112, v136
	v_add_f32_e32 v182, v113, v137
	v_mul_f32_e64 v187, |v177|, s76
	v_mul_f32_e64 v188, |v178|, s76
	v_mul_f32_e64 v189, |v179|, s76
	v_mul_f32_e64 v190, |v182|, s76
	v_fma_f32 v191, |v177|, s76, -v187
	v_fma_f32 v0, |v178|, s76, -v188
	v_fma_f32 v216, |v179|, s76, -v189
	v_fma_f32 v217, |v182|, s76, -v190
	v_rndne_f32_e32 v206, v187
	v_rndne_f32_e32 v207, v188
	v_rndne_f32_e32 v208, v189
	v_rndne_f32_e32 v209, v190
	v_fma_f32 v191, |v177|, s5, v191
	v_fma_f32 v0, |v178|, s5, v0
	v_fma_f32 v216, |v179|, s5, v216
	v_fma_f32 v217, |v182|, s5, v217
	v_sub_f32_e32 v187, v187, v206
	v_sub_f32_e32 v188, v188, v207
	v_sub_f32_e32 v189, v189, v208
	v_sub_f32_e32 v190, v190, v209
	v_add_f32_e32 v187, v187, v191
	v_add_f32_e32 v188, v188, v0
	v_add_f32_e32 v189, v189, v216
	v_add_f32_e32 v190, v190, v217
	v_cvt_i32_f32_e32 v206, v206
	v_cvt_i32_f32_e32 v207, v207
	v_cvt_i32_f32_e32 v208, v208
	v_cvt_i32_f32_e32 v209, v209
	v_exp_f32_e32 v183, v187
	v_exp_f32_e32 v184, v188
	v_exp_f32_e32 v185, v189
	v_exp_f32_e32 v186, v190
	v_ldexp_f32 v183, v183, v206
	v_ldexp_f32 v184, v184, v207
	v_ldexp_f32 v185, v185, v208
	v_ldexp_f32 v186, v186, v209
	v_add_f32_e32 v187, 1.0, v183
	v_add_f32_e32 v188, 1.0, v184
	v_add_f32_e32 v189, 1.0, v185
	v_add_f32_e32 v190, 1.0, v186
	v_add_f32_e32 v191, -1.0, v187
	v_add_f32_e32 v0, -1.0, v188
	v_add_f32_e32 v216, -1.0, v189
	v_add_f32_e32 v217, -1.0, v190
	v_log_f32_e32 v187, v187
	v_log_f32_e32 v188, v188
	v_log_f32_e32 v189, v189
	v_log_f32_e32 v190, v190
	v_rcp_f32_e32 v206, v191
	v_rcp_f32_e32 v207, v0
	v_rcp_f32_e32 v208, v216
	v_rcp_f32_e32 v209, v217
	v_mul_f32_e32 v210, v183, v206
	v_mul_f32_e32 v211, v184, v207
	v_mul_f32_e32 v212, v185, v208
	v_mul_f32_e32 v213, v186, v209
	v_fma_f32 v138, -v210, v191, v183
	v_fma_f32 v139, -v211, v0, v184
	v_fma_f32 v140, -v212, v216, v185
	v_fma_f32 v141, -v213, v217, v186
	v_fma_f32 v210, v138, v206, v210
	v_fma_f32 v211, v139, v207, v211
	v_fma_f32 v212, v140, v208, v212
	v_fma_f32 v213, v141, v209, v213
	v_mul_f32_e32 v206, s16, v187
	v_mul_f32_e32 v207, s16, v188
	v_mul_f32_e32 v208, s16, v189
	v_mul_f32_e32 v209, s16, v190
	v_fma_f32 v138, v187, s16, -v206
	v_fma_f32 v139, v188, s16, -v207
	v_fma_f32 v140, v189, s16, -v208
	v_fma_f32 v141, v190, s16, -v209
	v_fma_f32 v138, v187, s17, v138
	v_fma_f32 v139, v188, s17, v139
	v_fma_f32 v140, v189, s17, v140
	v_fma_f32 v141, v190, s17, v141
	v_add_f32_e32 v206, v206, v138
	v_add_f32_e32 v207, v207, v139
	v_add_f32_e32 v208, v208, v140
	v_add_f32_e32 v209, v209, v141
	v_mul_f32_e32 v206, v206, v210
	v_mul_f32_e32 v207, v207, v211
	v_mul_f32_e32 v208, v208, v212
	v_mul_f32_e32 v209, v209, v213
	v_min_f32_e32 v187, 0, v177
	v_min_f32_e32 v188, 0, v178
	v_min_f32_e32 v189, 0, v179
	v_min_f32_e32 v190, 0, v182
	v_cmp_eq_f32_e32 vcc, 0, v191
	s_nop 1
	v_cndmask_b32_e32 v206, v206, v183, vcc
	v_cmp_eq_f32_e32 vcc, 0, v0
	s_nop 1
	v_cndmask_b32_e32 v207, v207, v184, vcc
	v_cmp_eq_f32_e32 vcc, 0, v216
	s_nop 1
	v_cndmask_b32_e32 v208, v208, v185, vcc
	v_cmp_eq_f32_e32 vcc, 0, v217
	s_nop 1
	v_cndmask_b32_e32 v209, v209, v186, vcc
	v_sub_f32_e32 v138, v187, v206
	v_sub_f32_e32 v139, v188, v207
	v_sub_f32_e32 v140, v189, v208
	v_sub_f32_e32 v141, v190, v209
	v_add_f32_e32 v177, v106, v130
	v_add_f32_e32 v178, v107, v131
	v_add_f32_e32 v179, v108, v132
; __device__ __forceinline__ float log_sigmoid_(float x) { return fminf(x, 0.f) - log1pf(expf(-fabsf(x))); }
;     __device__ __forceinline__ void operator()(const f32x4 (&acc)[2][2][4][2], const pg8::Unit& u, int wr, int wc, int fr, int fq) const {
;     ...
;                     for (int m = 0; m < 4; ++m) { const int r = row0 + ai * 128 + m * 16; const f32x4 v0 = acc[ai][0][m][0] + b0, v1 = acc[ai][0][m][1] + b1;
;                         f32x4 l0, l1;
; #pragma unroll
;                         for (int j = 0; j < 4; ++j) { l0[j] = log_sigmoid_(v0[j]); l1[j] = log_sigmoid_(v1[j]); }
;                         float* dst = out + (smp ? O_FLS + (size_t)(r - MP) * 8 : O_FLP + (size_t)r * 8);
;                         *(f32x4*)dst = l0; *(f32x4*)(dst + 4) = l1; }
	v_add_f32_e32 v182, v109, v133
	v_mul_f32_e64 v187, |v177|, s76
	v_mul_f32_e64 v188, |v178|, s76
	v_mul_f32_e64 v189, |v179|, s76
	v_mul_f32_e64 v190, |v182|, s76
	v_fma_f32 v191, |v177|, s76, -v187
	v_fma_f32 v0, |v178|, s76, -v188
	v_fma_f32 v216, |v179|, s76, -v189
	v_fma_f32 v217, |v182|, s76, -v190
	v_rndne_f32_e32 v206, v187
	v_rndne_f32_e32 v207, v188
	v_rndne_f32_e32 v208, v189
	v_rndne_f32_e32 v209, v190
	v_fma_f32 v191, |v177|, s5, v191
	v_fma_f32 v0, |v178|, s5, v0
	v_fma_f32 v216, |v179|, s5, v216
	v_fma_f32 v217, |v182|, s5, v217
	v_sub_f32_e32 v187, v187, v206
	v_sub_f32_e32 v188, v188, v207
	v_sub_f32_e32 v189, v189, v208
	v_sub_f32_e32 v190, v190, v209
	v_add_f32_e32 v187, v187, v191
	v_add_f32_e32 v188, v188, v0
	v_add_f32_e32 v189, v189, v216
	v_add_f32_e32 v190, v190, v217
	v_cvt_i32_f32_e32 v206, v206
	v_cvt_i32_f32_e32 v207, v207
	v_cvt_i32_f32_e32 v208, v208
	v_cvt_i32_f32_e32 v209, v209
	v_exp_f32_e32 v183, v187
	v_exp_f32_e32 v184, v188
	v_exp_f32_e32 v185, v189
	v_exp_f32_e32 v186, v190
	v_ldexp_f32 v183, v183, v206
	v_ldexp_f32 v184, v184, v207
	v_ldexp_f32 v185, v185, v208
	v_ldexp_f32 v186, v186, v209
	v_add_f32_e32 v187, 1.0, v183
	v_add_f32_e32 v188, 1.0, v184
	v_add_f32_e32 v189, 1.0, v185
	v_add_f32_e32 v190, 1.0, v186
	v_add_f32_e32 v191, -1.0, v187
	v_add_f32_e32 v0, -1.0, v188
	v_add_f32_e32 v216, -1.0, v189
	v_add_f32_e32 v217, -1.0, v190
	v_log_f32_e32 v187, v187
	v_log_f32_e32 v188, v188
	v_log_f32_e32 v189, v189
	v_log_f32_e32 v190, v190
	v_rcp_f32_e32 v206, v191
	v_rcp_f32_e32 v207, v0
	v_rcp_f32_e32 v208, v216
	v_rcp_f32_e32 v209, v217
	v_mul_f32_e32 v210, v183, v206
	v_mul_f32_e32 v211, v184, v207
	v_mul_f32_e32 v212, v185, v208
	v_mul_f32_e32 v213, v186, v209
	v_fma_f32 v142, -v210, v191, v183
	v_fma_f32 v143, -v211, v0, v184
	v_fma_f32 v144, -v212, v216, v185
	v_fma_f32 v145, -v213, v217, v186
	v_fma_f32 v210, v142, v206, v210
	v_fma_f32 v211, v143, v207, v211
	v_fma_f32 v212, v144, v208, v212
	v_fma_f32 v213, v145, v209, v213
	v_mul_f32_e32 v206, s16, v187
	v_mul_f32_e32 v207, s16, v188
	v_mul_f32_e32 v208, s16, v189
	v_mul_f32_e32 v209, s16, v190
	v_fma_f32 v142, v187, s16, -v206
	v_fma_f32 v143, v188, s16, -v207
	v_fma_f32 v144, v189, s16, -v208
	v_fma_f32 v145, v190, s16, -v209
	v_fma_f32 v142, v187, s17, v142
	v_fma_f32 v143, v188, s17, v143
	v_fma_f32 v144, v189, s17, v144
	v_fma_f32 v145, v190, s17, v145
	v_add_f32_e32 v206, v206, v142
	v_add_f32_e32 v207, v207, v143
	v_add_f32_e32 v208, v208, v144
	v_add_f32_e32 v209, v209, v145
	v_mul_f32_e32 v206, v206, v210
	v_mul_f32_e32 v207, v207, v211
	v_mul_f32_e32 v208, v208, v212
	v_mul_f32_e32 v209, v209, v213
	v_min_f32_e32 v187, 0, v177
	v_min_f32_e32 v188, 0, v178
	v_min_f32_e32 v189, 0, v179
	v_min_f32_e32 v190, 0, v182
	v_cmp_eq_f32_e32 vcc, 0, v191
	s_nop 1
	v_cndmask_b32_e32 v206, v206, v183, vcc
	v_cmp_eq_f32_e32 vcc, 0, v0
	s_nop 1
	v_cndmask_b32_e32 v207, v207, v184, vcc
	v_cmp_eq_f32_e32 vcc, 0, v216
	s_nop 1
	v_cndmask_b32_e32 v208, v208, v185, vcc
	v_cmp_eq_f32_e32 vcc, 0, v217
	s_nop 1
	v_cndmask_b32_e32 v209, v209, v186, vcc
	v_sub_f32_e32 v142, v187, v206
	v_sub_f32_e32 v143, v188, v207
	v_sub_f32_e32 v144, v189, v208
	v_sub_f32_e32 v145, v190, v209
	global_store_dwordx4 v[146:147], v[138:141], off offset:512
	global_store_dwordx4 v[146:147], v[142:145], off offset:528
	s_nop 1
	v_add_f32_e32 v177, v94, v134
	v_add_f32_e32 v178, v95, v135
	v_add_f32_e32 v179, v96, v136
	v_add_f32_e32 v182, v97, v137
	v_mul_f32_e64 v187, |v177|, s76
	v_mul_f32_e64 v188, |v178|, s76
	v_mul_f32_e64 v189, |v179|, s76
	v_mul_f32_e64 v190, |v182|, s76
	v_fma_f32 v191, |v177|, s76, -v187
	v_fma_f32 v0, |v178|, s76, -v188
	v_fma_f32 v216, |v179|, s76, -v189
	v_fma_f32 v217, |v182|, s76, -v190
	v_rndne_f32_e32 v206, v187
	v_rndne_f32_e32 v207, v188
	v_rndne_f32_e32 v208, v189
	v_rndne_f32_e32 v209, v190
	v_fma_f32 v191, |v177|, s5, v191
	v_fma_f32 v0, |v178|, s5, v0
	v_fma_f32 v216, |v179|, s5, v216
	v_fma_f32 v217, |v182|, s5, v217
	v_sub_f32_e32 v187, v187, v206
	v_sub_f32_e32 v188, v188, v207
	v_sub_f32_e32 v189, v189, v208
	v_sub_f32_e32 v190, v190, v209
	v_add_f32_e32 v187, v187, v191
	v_add_f32_e32 v188, v188, v0
	v_add_f32_e32 v189, v189, v216
	v_add_f32_e32 v190, v190, v217
	v_cvt_i32_f32_e32 v206, v206
	v_cvt_i32_f32_e32 v207, v207
	v_cvt_i32_f32_e32 v208, v208
	v_cvt_i32_f32_e32 v209, v209
	v_exp_f32_e32 v183, v187
	v_exp_f32_e32 v184, v188
	v_exp_f32_e32 v185, v189
	v_exp_f32_e32 v186, v190
	v_ldexp_f32 v183, v183, v206
	v_ldexp_f32 v184, v184, v207
	v_ldexp_f32 v185, v185, v208
	v_ldexp_f32 v186, v186, v209
	v_add_f32_e32 v187, 1.0, v183
	v_add_f32_e32 v188, 1.0, v184
	v_add_f32_e32 v189, 1.0, v185
	v_add_f32_e32 v190, 1.0, v186
	v_add_f32_e32 v191, -1.0, v187
	v_add_f32_e32 v0, -1.0, v188
	v_add_f32_e32 v216, -1.0, v189
	v_add_f32_e32 v217, -1.0, v190
	v_log_f32_e32 v187, v187
	v_log_f32_e32 v188, v188
	v_log_f32_e32 v189, v189
	v_log_f32_e32 v190, v190
	v_rcp_f32_e32 v206, v191
	v_rcp_f32_e32 v207, v0
	v_rcp_f32_e32 v208, v216
	v_rcp_f32_e32 v209, v217
	v_mul_f32_e32 v210, v183, v206
	v_mul_f32_e32 v211, v184, v207
	v_mul_f32_e32 v212, v185, v208
	v_mul_f32_e32 v213, v186, v209
	v_fma_f32 v138, -v210, v191, v183
	v_fma_f32 v139, -v211, v0, v184
	v_fma_f32 v140, -v212, v216, v185
	v_fma_f32 v141, -v213, v217, v186
	v_fma_f32 v210, v138, v206, v210
	v_fma_f32 v211, v139, v207, v211
	v_fma_f32 v212, v140, v208, v212
	v_fma_f32 v213, v141, v209, v213
	v_mul_f32_e32 v206, s16, v187
	v_mul_f32_e32 v207, s16, v188
	v_mul_f32_e32 v208, s16, v189
	v_mul_f32_e32 v209, s16, v190
	v_fma_f32 v138, v187, s16, -v206
	v_fma_f32 v139, v188, s16, -v207
; __device__ __forceinline__ float log_sigmoid_(float x) { return fminf(x, 0.f) - log1pf(expf(-fabsf(x))); }
;     __device__ __forceinline__ void operator()(const f32x4 (&acc)[2][2][4][2], const pg8::Unit& u, int wr, int wc, int fr, int fq) const {
;     ...
;                     for (int m = 0; m < 4; ++m) { const int r = row0 + ai * 128 + m * 16; const f32x4 v0 = acc[ai][0][m][0] + b0, v1 = acc[ai][0][m][1] + b1;
;                         f32x4 l0, l1;
; #pragma unroll
;                         for (int j = 0; j < 4; ++j) { l0[j] = log_sigmoid_(v0[j]); l1[j] = log_sigmoid_(v1[j]); }
;                         float* dst = out + (smp ? O_FLS + (size_t)(r - MP) * 8 : O_FLP + (size_t)r * 8);
;                         *(f32x4*)dst = l0; *(f32x4*)(dst + 4) = l1; }
	v_fma_f32 v140, v189, s16, -v208
	v_fma_f32 v141, v190, s16, -v209
	v_fma_f32 v138, v187, s17, v138
	v_fma_f32 v139, v188, s17, v139
	v_fma_f32 v140, v189, s17, v140
	v_fma_f32 v141, v190, s17, v141
	v_add_f32_e32 v206, v206, v138
	v_add_f32_e32 v207, v207, v139
	v_add_f32_e32 v208, v208, v140
	v_add_f32_e32 v209, v209, v141
	v_mul_f32_e32 v206, v206, v210
	v_mul_f32_e32 v207, v207, v211
	v_mul_f32_e32 v208, v208, v212
	v_mul_f32_e32 v209, v209, v213
	v_min_f32_e32 v187, 0, v177
	v_min_f32_e32 v188, 0, v178
	v_min_f32_e32 v189, 0, v179
	v_min_f32_e32 v190, 0, v182
	v_cmp_eq_f32_e32 vcc, 0, v191
	s_nop 1
	v_cndmask_b32_e32 v206, v206, v183, vcc
	v_cmp_eq_f32_e32 vcc, 0, v0
	s_nop 1
	v_cndmask_b32_e32 v207, v207, v184, vcc
	v_cmp_eq_f32_e32 vcc, 0, v216
	s_nop 1
	v_cndmask_b32_e32 v208, v208, v185, vcc
	v_cmp_eq_f32_e32 vcc, 0, v217
	s_nop 1
	v_cndmask_b32_e32 v209, v209, v186, vcc
	v_sub_f32_e32 v138, v187, v206
	v_sub_f32_e32 v139, v188, v207
	v_sub_f32_e32 v140, v189, v208
	v_sub_f32_e32 v141, v190, v209
	v_add_f32_e32 v177, v90, v130
	v_add_f32_e32 v178, v91, v131
	v_add_f32_e32 v179, v92, v132
	v_add_f32_e32 v182, v93, v133
	v_mul_f32_e64 v187, |v177|, s76
	v_mul_f32_e64 v188, |v178|, s76
	v_mul_f32_e64 v189, |v179|, s76
	v_mul_f32_e64 v190, |v182|, s76
	v_fma_f32 v191, |v177|, s76, -v187
	v_fma_f32 v0, |v178|, s76, -v188
	v_fma_f32 v216, |v179|, s76, -v189
	v_fma_f32 v217, |v182|, s76, -v190
	v_rndne_f32_e32 v206, v187
	v_rndne_f32_e32 v207, v188
	v_rndne_f32_e32 v208, v189
	v_rndne_f32_e32 v209, v190
	v_fma_f32 v191, |v177|, s5, v191
	v_fma_f32 v0, |v178|, s5, v0
	v_fma_f32 v216, |v179|, s5, v216
	v_fma_f32 v217, |v182|, s5, v217
	v_sub_f32_e32 v187, v187, v206
	v_sub_f32_e32 v188, v188, v207
	v_sub_f32_e32 v189, v189, v208
	v_sub_f32_e32 v190, v190, v209
	v_add_f32_e32 v187, v187, v191
	v_add_f32_e32 v188, v188, v0
	v_add_f32_e32 v189, v189, v216
	v_add_f32_e32 v190, v190, v217
	v_cvt_i32_f32_e32 v206, v206
	v_cvt_i32_f32_e32 v207, v207
	v_cvt_i32_f32_e32 v208, v208
	v_cvt_i32_f32_e32 v209, v209
	v_exp_f32_e32 v183, v187
	v_exp_f32_e32 v184, v188
	v_exp_f32_e32 v185, v189
	v_exp_f32_e32 v186, v190
	v_ldexp_f32 v183, v183, v206
	v_ldexp_f32 v184, v184, v207
	v_ldexp_f32 v185, v185, v208
	v_ldexp_f32 v186, v186, v209
	v_add_f32_e32 v187, 1.0, v183
	v_add_f32_e32 v188, 1.0, v184
	v_add_f32_e32 v189, 1.0, v185
	v_add_f32_e32 v190, 1.0, v186
	v_add_f32_e32 v191, -1.0, v187
	v_add_f32_e32 v0, -1.0, v188
	v_add_f32_e32 v216, -1.0, v189
	v_add_f32_e32 v217, -1.0, v190
	v_log_f32_e32 v187, v187
	v_log_f32_e32 v188, v188
	v_log_f32_e32 v189, v189
	v_log_f32_e32 v190, v190
	v_rcp_f32_e32 v206, v191
	v_rcp_f32_e32 v207, v0
	v_rcp_f32_e32 v208, v216
	v_rcp_f32_e32 v209, v217
	v_mul_f32_e32 v210, v183, v206
	v_mul_f32_e32 v211, v184, v207
	v_mul_f32_e32 v212, v185, v208
	v_mul_f32_e32 v213, v186, v209
	v_fma_f32 v142, -v210, v191, v183
	v_fma_f32 v143, -v211, v0, v184
	v_fma_f32 v144, -v212, v216, v185
	v_fma_f32 v145, -v213, v217, v186
	v_fma_f32 v210, v142, v206, v210
	v_fma_f32 v211, v143, v207, v211
	v_fma_f32 v212, v144, v208, v212
	v_fma_f32 v213, v145, v209, v213
	v_mul_f32_e32 v206, s16, v187
	v_mul_f32_e32 v207, s16, v188
	v_mul_f32_e32 v208, s16, v189
	v_mul_f32_e32 v209, s16, v190
	v_fma_f32 v142, v187, s16, -v206
	v_fma_f32 v143, v188, s16, -v207
	v_fma_f32 v144, v189, s16, -v208
	v_fma_f32 v145, v190, s16, -v209
	v_fma_f32 v142, v187, s17, v142
	v_fma_f32 v143, v188, s17, v143
	v_fma_f32 v144, v189, s17, v144
	v_fma_f32 v145, v190, s17, v145
	v_add_f32_e32 v206, v206, v142
	v_add_f32_e32 v207, v207, v143
	v_add_f32_e32 v208, v208, v144
	v_add_f32_e32 v209, v209, v145
	v_mul_f32_e32 v206, v206, v210
	v_mul_f32_e32 v207, v207, v211
	v_mul_f32_e32 v208, v208, v212
	v_mul_f32_e32 v209, v209, v213
	v_min_f32_e32 v187, 0, v177
	v_min_f32_e32 v188, 0, v178
	v_min_f32_e32 v189, 0, v179
	v_min_f32_e32 v190, 0, v182
	v_cmp_eq_f32_e32 vcc, 0, v191
	s_nop 1
	v_cndmask_b32_e32 v206, v206, v183, vcc
	v_cmp_eq_f32_e32 vcc, 0, v0
	s_nop 1
	v_cndmask_b32_e32 v207, v207, v184, vcc
	v_cmp_eq_f32_e32 vcc, 0, v216
	s_nop 1
	v_cndmask_b32_e32 v208, v208, v185, vcc
	v_cmp_eq_f32_e32 vcc, 0, v217
	s_nop 1
	v_cndmask_b32_e32 v209, v209, v186, vcc
	v_sub_f32_e32 v142, v187, v206
	v_sub_f32_e32 v143, v188, v207
	v_sub_f32_e32 v144, v189, v208
	v_sub_f32_e32 v145, v190, v209
	global_store_dwordx4 v[146:147], v[138:141], off offset:1024
	global_store_dwordx4 v[146:147], v[142:145], off offset:1040
	s_nop 1
	v_add_f32_e32 v177, v78, v134
	v_add_f32_e32 v178, v79, v135
	v_add_f32_e32 v179, v80, v136
	v_add_f32_e32 v182, v81, v137
	v_mul_f32_e64 v187, |v177|, s76
	v_mul_f32_e64 v188, |v178|, s76
	v_mul_f32_e64 v189, |v179|, s76
	v_mul_f32_e64 v190, |v182|, s76
	v_fma_f32 v191, |v177|, s76, -v187
	v_fma_f32 v0, |v178|, s76, -v188
	v_fma_f32 v216, |v179|, s76, -v189
	v_fma_f32 v217, |v182|, s76, -v190
	v_rndne_f32_e32 v206, v187
	v_rndne_f32_e32 v207, v188
	v_rndne_f32_e32 v208, v189
	v_rndne_f32_e32 v209, v190
	v_fma_f32 v191, |v177|, s5, v191
	v_fma_f32 v0, |v178|, s5, v0
	v_fma_f32 v216, |v179|, s5, v216
	v_fma_f32 v217, |v182|, s5, v217
	v_sub_f32_e32 v187, v187, v206
	v_sub_f32_e32 v188, v188, v207
	v_sub_f32_e32 v189, v189, v208
	v_sub_f32_e32 v190, v190, v209
	v_add_f32_e32 v187, v187, v191
	v_add_f32_e32 v188, v188, v0
	v_add_f32_e32 v189, v189, v216
	v_add_f32_e32 v190, v190, v217
	v_cvt_i32_f32_e32 v206, v206
	v_cvt_i32_f32_e32 v207, v207
	v_cvt_i32_f32_e32 v208, v208
	v_cvt_i32_f32_e32 v209, v209
	v_exp_f32_e32 v183, v187
	v_exp_f32_e32 v184, v188
	v_exp_f32_e32 v185, v189
	v_exp_f32_e32 v186, v190
	v_ldexp_f32 v183, v183, v206
	v_ldexp_f32 v184, v184, v207
; __device__ __forceinline__ float log_sigmoid_(float x) { return fminf(x, 0.f) - log1pf(expf(-fabsf(x))); }
;     __device__ __forceinline__ void operator()(const f32x4 (&acc)[2][2][4][2], const pg8::Unit& u, int wr, int wc, int fr, int fq) const {
;     ...
;                     for (int m = 0; m < 4; ++m) { const int r = row0 + ai * 128 + m * 16; const f32x4 v0 = acc[ai][0][m][0] + b0, v1 = acc[ai][0][m][1] + b1;
;                         f32x4 l0, l1;
; #pragma unroll
;                         for (int j = 0; j < 4; ++j) { l0[j] = log_sigmoid_(v0[j]); l1[j] = log_sigmoid_(v1[j]); }
;                         float* dst = out + (smp ? O_FLS + (size_t)(r - MP) * 8 : O_FLP + (size_t)r * 8);
;                         *(f32x4*)dst = l0; *(f32x4*)(dst + 4) = l1; }
	v_ldexp_f32 v185, v185, v208
	v_ldexp_f32 v186, v186, v209
	v_add_f32_e32 v187, 1.0, v183
	v_add_f32_e32 v188, 1.0, v184
	v_add_f32_e32 v189, 1.0, v185
	v_add_f32_e32 v190, 1.0, v186
	v_add_f32_e32 v191, -1.0, v187
	v_add_f32_e32 v0, -1.0, v188
	v_add_f32_e32 v216, -1.0, v189
	v_add_f32_e32 v217, -1.0, v190
	v_log_f32_e32 v187, v187
	v_log_f32_e32 v188, v188
	v_log_f32_e32 v189, v189
	v_log_f32_e32 v190, v190
	v_rcp_f32_e32 v206, v191
	v_rcp_f32_e32 v207, v0
	v_rcp_f32_e32 v208, v216
	v_rcp_f32_e32 v209, v217
	v_mul_f32_e32 v210, v183, v206
	v_mul_f32_e32 v211, v184, v207
	v_mul_f32_e32 v212, v185, v208
	v_mul_f32_e32 v213, v186, v209
	v_fma_f32 v138, -v210, v191, v183
	v_fma_f32 v139, -v211, v0, v184
	v_fma_f32 v140, -v212, v216, v185
	v_fma_f32 v141, -v213, v217, v186
	v_fma_f32 v210, v138, v206, v210
	v_fma_f32 v211, v139, v207, v211
	v_fma_f32 v212, v140, v208, v212
	v_fma_f32 v213, v141, v209, v213
	v_mul_f32_e32 v206, s16, v187
	v_mul_f32_e32 v207, s16, v188
	v_mul_f32_e32 v208, s16, v189
	v_mul_f32_e32 v209, s16, v190
	v_fma_f32 v138, v187, s16, -v206
	v_fma_f32 v139, v188, s16, -v207
	v_fma_f32 v140, v189, s16, -v208
	v_fma_f32 v141, v190, s16, -v209
	v_fma_f32 v138, v187, s17, v138
	v_fma_f32 v139, v188, s17, v139
	v_fma_f32 v140, v189, s17, v140
	v_fma_f32 v141, v190, s17, v141
	v_add_f32_e32 v206, v206, v138
	v_add_f32_e32 v207, v207, v139
	v_add_f32_e32 v208, v208, v140
	v_add_f32_e32 v209, v209, v141
	v_mul_f32_e32 v206, v206, v210
	v_mul_f32_e32 v207, v207, v211
	v_mul_f32_e32 v208, v208, v212
	v_mul_f32_e32 v209, v209, v213
	v_min_f32_e32 v187, 0, v177
	v_min_f32_e32 v188, 0, v178
	v_min_f32_e32 v189, 0, v179
	v_min_f32_e32 v190, 0, v182
	v_cmp_eq_f32_e32 vcc, 0, v191
	s_nop 1
	v_cndmask_b32_e32 v206, v206, v183, vcc
	v_cmp_eq_f32_e32 vcc, 0, v0
	s_nop 1
	v_cndmask_b32_e32 v207, v207, v184, vcc
	v_cmp_eq_f32_e32 vcc, 0, v216
	s_nop 1
	v_cndmask_b32_e32 v208, v208, v185, vcc
	v_cmp_eq_f32_e32 vcc, 0, v217
	s_nop 1
	v_cndmask_b32_e32 v209, v209, v186, vcc
	v_sub_f32_e32 v138, v187, v206
	v_sub_f32_e32 v139, v188, v207
	v_sub_f32_e32 v140, v189, v208
	v_sub_f32_e32 v141, v190, v209
	v_add_f32_e32 v177, v74, v130
	v_add_f32_e32 v178, v75, v131
	v_add_f32_e32 v179, v76, v132
	v_add_f32_e32 v182, v77, v133
	v_mul_f32_e64 v187, |v177|, s76
	v_mul_f32_e64 v188, |v178|, s76
	v_mul_f32_e64 v189, |v179|, s76
	v_mul_f32_e64 v190, |v182|, s76
	v_fma_f32 v191, |v177|, s76, -v187
	v_fma_f32 v0, |v178|, s76, -v188
	v_fma_f32 v216, |v179|, s76, -v189
	v_fma_f32 v217, |v182|, s76, -v190
	v_rndne_f32_e32 v206, v187
	v_rndne_f32_e32 v207, v188
	v_rndne_f32_e32 v208, v189
	v_rndne_f32_e32 v209, v190
	v_fma_f32 v191, |v177|, s5, v191
	v_fma_f32 v0, |v178|, s5, v0
	v_fma_f32 v216, |v179|, s5, v216
	v_fma_f32 v217, |v182|, s5, v217
	v_sub_f32_e32 v187, v187, v206
	v_sub_f32_e32 v188, v188, v207
	v_sub_f32_e32 v189, v189, v208
	v_sub_f32_e32 v190, v190, v209
	v_add_f32_e32 v187, v187, v191
	v_add_f32_e32 v188, v188, v0
	v_add_f32_e32 v189, v189, v216
	v_add_f32_e32 v190, v190, v217
	v_cvt_i32_f32_e32 v206, v206
	v_cvt_i32_f32_e32 v207, v207
	v_cvt_i32_f32_e32 v208, v208
	v_cvt_i32_f32_e32 v209, v209
	v_exp_f32_e32 v183, v187
	v_exp_f32_e32 v184, v188
	v_exp_f32_e32 v185, v189
	v_exp_f32_e32 v186, v190
	v_ldexp_f32 v183, v183, v206
	v_ldexp_f32 v184, v184, v207
	v_ldexp_f32 v185, v185, v208
	v_ldexp_f32 v186, v186, v209
	v_add_f32_e32 v187, 1.0, v183
	v_add_f32_e32 v188, 1.0, v184
	v_add_f32_e32 v189, 1.0, v185
	v_add_f32_e32 v190, 1.0, v186
	v_add_f32_e32 v191, -1.0, v187
	v_add_f32_e32 v0, -1.0, v188
	v_add_f32_e32 v216, -1.0, v189
	v_add_f32_e32 v217, -1.0, v190
	v_log_f32_e32 v187, v187
	v_log_f32_e32 v188, v188
	v_log_f32_e32 v189, v189
	v_log_f32_e32 v190, v190
	v_rcp_f32_e32 v206, v191
	v_rcp_f32_e32 v207, v0
	v_rcp_f32_e32 v208, v216
	v_rcp_f32_e32 v209, v217
	v_mul_f32_e32 v210, v183, v206
	v_mul_f32_e32 v211, v184, v207
	v_mul_f32_e32 v212, v185, v208
	v_mul_f32_e32 v213, v186, v209
	v_fma_f32 v142, -v210, v191, v183
	v_fma_f32 v143, -v211, v0, v184
	v_fma_f32 v144, -v212, v216, v185
	v_fma_f32 v145, -v213, v217, v186
	v_fma_f32 v210, v142, v206, v210
	v_fma_f32 v211, v143, v207, v211
	v_fma_f32 v212, v144, v208, v212
	v_fma_f32 v213, v145, v209, v213
	v_mul_f32_e32 v206, s16, v187
	v_mul_f32_e32 v207, s16, v188
	v_mul_f32_e32 v208, s16, v189
	v_mul_f32_e32 v209, s16, v190
	v_fma_f32 v142, v187, s16, -v206
	v_fma_f32 v143, v188, s16, -v207
	v_fma_f32 v144, v189, s16, -v208
	v_fma_f32 v145, v190, s16, -v209
	v_fma_f32 v142, v187, s17, v142
	v_fma_f32 v143, v188, s17, v143
	v_fma_f32 v144, v189, s17, v144
	v_fma_f32 v145, v190, s17, v145
	v_add_f32_e32 v206, v206, v142
	v_add_f32_e32 v207, v207, v143
	v_add_f32_e32 v208, v208, v144
	v_add_f32_e32 v209, v209, v145
	v_mul_f32_e32 v206, v206, v210
	v_mul_f32_e32 v207, v207, v211
	v_mul_f32_e32 v208, v208, v212
	v_mul_f32_e32 v209, v209, v213
	v_min_f32_e32 v187, 0, v177
	v_min_f32_e32 v188, 0, v178
	v_min_f32_e32 v189, 0, v179
	v_min_f32_e32 v190, 0, v182
	v_cmp_eq_f32_e32 vcc, 0, v191
	s_nop 1
	v_cndmask_b32_e32 v206, v206, v183, vcc
	v_cmp_eq_f32_e32 vcc, 0, v0
	s_nop 1
	v_cndmask_b32_e32 v207, v207, v184, vcc
	v_cmp_eq_f32_e32 vcc, 0, v216
	s_nop 1
	v_cndmask_b32_e32 v208, v208, v185, vcc
	v_cmp_eq_f32_e32 vcc, 0, v217
	s_nop 1
	v_cndmask_b32_e32 v209, v209, v186, vcc
	v_sub_f32_e32 v142, v187, v206
	v_sub_f32_e32 v143, v188, v207
	v_sub_f32_e32 v144, v189, v208
	v_sub_f32_e32 v145, v190, v209
	global_store_dwordx4 v[146:147], v[138:141], off offset:1536
	global_store_dwordx4 v[146:147], v[142:145], off offset:1552
	s_nop 1
	v_add_f32_e32 v177, v62, v134
	v_add_f32_e32 v178, v63, v135
; __device__ __forceinline__ float log_sigmoid_(float x) { return fminf(x, 0.f) - log1pf(expf(-fabsf(x))); }
;     __device__ __forceinline__ void operator()(const f32x4 (&acc)[2][2][4][2], const pg8::Unit& u, int wr, int wc, int fr, int fq) const {
;     ...
;                     for (int m = 0; m < 4; ++m) { const int r = row0 + ai * 128 + m * 16; const f32x4 v0 = acc[ai][0][m][0] + b0, v1 = acc[ai][0][m][1] + b1;
;                         f32x4 l0, l1;
; #pragma unroll
;                         for (int j = 0; j < 4; ++j) { l0[j] = log_sigmoid_(v0[j]); l1[j] = log_sigmoid_(v1[j]); }
;                         float* dst = out + (smp ? O_FLS + (size_t)(r - MP) * 8 : O_FLP + (size_t)r * 8);
;                         *(f32x4*)dst = l0; *(f32x4*)(dst + 4) = l1; }
	v_add_f32_e32 v179, v64, v136
	v_add_f32_e32 v182, v65, v137
	v_mul_f32_e64 v187, |v177|, s76
	v_mul_f32_e64 v188, |v178|, s76
	v_mul_f32_e64 v189, |v179|, s76
	v_mul_f32_e64 v190, |v182|, s76
	v_fma_f32 v191, |v177|, s76, -v187
	v_fma_f32 v0, |v178|, s76, -v188
	v_fma_f32 v216, |v179|, s76, -v189
	v_fma_f32 v217, |v182|, s76, -v190
	v_rndne_f32_e32 v206, v187
	v_rndne_f32_e32 v207, v188
	v_rndne_f32_e32 v208, v189
	v_rndne_f32_e32 v209, v190
	v_fma_f32 v191, |v177|, s5, v191
	v_fma_f32 v0, |v178|, s5, v0
	v_fma_f32 v216, |v179|, s5, v216
	v_fma_f32 v217, |v182|, s5, v217
	v_sub_f32_e32 v187, v187, v206
	v_sub_f32_e32 v188, v188, v207
	v_sub_f32_e32 v189, v189, v208
	v_sub_f32_e32 v190, v190, v209
	v_add_f32_e32 v187, v187, v191
	v_add_f32_e32 v188, v188, v0
	v_add_f32_e32 v189, v189, v216
	v_add_f32_e32 v190, v190, v217
	v_cvt_i32_f32_e32 v206, v206
	v_cvt_i32_f32_e32 v207, v207
	v_cvt_i32_f32_e32 v208, v208
	v_cvt_i32_f32_e32 v209, v209
	v_exp_f32_e32 v183, v187
	v_exp_f32_e32 v184, v188
	v_exp_f32_e32 v185, v189
	v_exp_f32_e32 v186, v190
	v_ldexp_f32 v183, v183, v206
	v_ldexp_f32 v184, v184, v207
	v_ldexp_f32 v185, v185, v208
	v_ldexp_f32 v186, v186, v209
	v_add_f32_e32 v187, 1.0, v183
	v_add_f32_e32 v188, 1.0, v184
	v_add_f32_e32 v189, 1.0, v185
	v_add_f32_e32 v190, 1.0, v186
	v_add_f32_e32 v191, -1.0, v187
	v_add_f32_e32 v0, -1.0, v188
	v_add_f32_e32 v216, -1.0, v189
	v_add_f32_e32 v217, -1.0, v190
	v_log_f32_e32 v187, v187
	v_log_f32_e32 v188, v188
	v_log_f32_e32 v189, v189
	v_log_f32_e32 v190, v190
	v_rcp_f32_e32 v206, v191
	v_rcp_f32_e32 v207, v0
	v_rcp_f32_e32 v208, v216
	v_rcp_f32_e32 v209, v217
	v_mul_f32_e32 v210, v183, v206
	v_mul_f32_e32 v211, v184, v207
	v_mul_f32_e32 v212, v185, v208
	v_mul_f32_e32 v213, v186, v209
	v_fma_f32 v138, -v210, v191, v183
	v_fma_f32 v139, -v211, v0, v184
	v_fma_f32 v140, -v212, v216, v185
	v_fma_f32 v141, -v213, v217, v186
	v_fma_f32 v210, v138, v206, v210
	v_fma_f32 v211, v139, v207, v211
	v_fma_f32 v212, v140, v208, v212
	v_fma_f32 v213, v141, v209, v213
	v_mul_f32_e32 v206, s16, v187
	v_mul_f32_e32 v207, s16, v188
	v_mul_f32_e32 v208, s16, v189
	v_mul_f32_e32 v209, s16, v190
	v_fma_f32 v138, v187, s16, -v206
	v_fma_f32 v139, v188, s16, -v207
	v_fma_f32 v140, v189, s16, -v208
	v_fma_f32 v141, v190, s16, -v209
	v_fma_f32 v138, v187, s17, v138
	v_fma_f32 v139, v188, s17, v139
	v_fma_f32 v140, v189, s17, v140
	v_fma_f32 v141, v190, s17, v141
	v_add_f32_e32 v206, v206, v138
	v_add_f32_e32 v207, v207, v139
	v_add_f32_e32 v208, v208, v140
	v_add_f32_e32 v209, v209, v141
	v_mul_f32_e32 v206, v206, v210
	v_mul_f32_e32 v207, v207, v211
	v_mul_f32_e32 v208, v208, v212
	v_mul_f32_e32 v209, v209, v213
	v_min_f32_e32 v187, 0, v177
	v_min_f32_e32 v188, 0, v178
	v_min_f32_e32 v189, 0, v179
	v_min_f32_e32 v190, 0, v182
	v_cmp_eq_f32_e32 vcc, 0, v191
	s_nop 1
	v_cndmask_b32_e32 v206, v206, v183, vcc
	v_cmp_eq_f32_e32 vcc, 0, v0
	s_nop 1
	v_cndmask_b32_e32 v207, v207, v184, vcc
	v_cmp_eq_f32_e32 vcc, 0, v216
	s_nop 1
	v_cndmask_b32_e32 v208, v208, v185, vcc
	v_cmp_eq_f32_e32 vcc, 0, v217
	s_nop 1
	v_cndmask_b32_e32 v209, v209, v186, vcc
	v_sub_f32_e32 v138, v187, v206
	v_sub_f32_e32 v139, v188, v207
	v_sub_f32_e32 v140, v189, v208
	v_sub_f32_e32 v141, v190, v209
	v_add_f32_e32 v177, v58, v130
	v_add_f32_e32 v178, v59, v131
	v_add_f32_e32 v179, v60, v132
	v_add_f32_e32 v182, v61, v133
	v_mul_f32_e64 v187, |v177|, s76
	v_mul_f32_e64 v188, |v178|, s76
	v_mul_f32_e64 v189, |v179|, s76
	v_mul_f32_e64 v190, |v182|, s76
	v_fma_f32 v191, |v177|, s76, -v187
	v_fma_f32 v0, |v178|, s76, -v188
	v_fma_f32 v216, |v179|, s76, -v189
	v_fma_f32 v217, |v182|, s76, -v190
	v_rndne_f32_e32 v206, v187
	v_rndne_f32_e32 v207, v188
	v_rndne_f32_e32 v208, v189
	v_rndne_f32_e32 v209, v190
	v_fma_f32 v191, |v177|, s5, v191
	v_fma_f32 v0, |v178|, s5, v0
	v_fma_f32 v216, |v179|, s5, v216
	v_fma_f32 v217, |v182|, s5, v217
	v_sub_f32_e32 v187, v187, v206
	v_sub_f32_e32 v188, v188, v207
	v_sub_f32_e32 v189, v189, v208
	v_sub_f32_e32 v190, v190, v209
	v_add_f32_e32 v187, v187, v191
	v_add_f32_e32 v188, v188, v0
	v_add_f32_e32 v189, v189, v216
	v_add_f32_e32 v190, v190, v217
	v_cvt_i32_f32_e32 v206, v206
	v_cvt_i32_f32_e32 v207, v207
	v_cvt_i32_f32_e32 v208, v208
	v_cvt_i32_f32_e32 v209, v209
	v_exp_f32_e32 v183, v187
	v_exp_f32_e32 v184, v188
	v_exp_f32_e32 v185, v189
	v_exp_f32_e32 v186, v190
	v_ldexp_f32 v183, v183, v206
	v_ldexp_f32 v184, v184, v207
	v_ldexp_f32 v185, v185, v208
	v_ldexp_f32 v186, v186, v209
	v_add_f32_e32 v187, 1.0, v183
	v_add_f32_e32 v188, 1.0, v184
	v_add_f32_e32 v189, 1.0, v185
	v_add_f32_e32 v190, 1.0, v186
	v_add_f32_e32 v191, -1.0, v187
	v_add_f32_e32 v0, -1.0, v188
	v_add_f32_e32 v216, -1.0, v189
	v_add_f32_e32 v217, -1.0, v190
	v_log_f32_e32 v187, v187
	v_log_f32_e32 v188, v188
	v_log_f32_e32 v189, v189
	v_log_f32_e32 v190, v190
	v_rcp_f32_e32 v206, v191
	v_rcp_f32_e32 v207, v0
	v_rcp_f32_e32 v208, v216
	v_rcp_f32_e32 v209, v217
	v_mul_f32_e32 v210, v183, v206
	v_mul_f32_e32 v211, v184, v207
	v_mul_f32_e32 v212, v185, v208
	v_mul_f32_e32 v213, v186, v209
	v_fma_f32 v142, -v210, v191, v183
	v_fma_f32 v143, -v211, v0, v184
	v_fma_f32 v144, -v212, v216, v185
	v_fma_f32 v145, -v213, v217, v186
	v_fma_f32 v210, v142, v206, v210
	v_fma_f32 v211, v143, v207, v211
	v_fma_f32 v212, v144, v208, v212
	v_fma_f32 v213, v145, v209, v213
	v_mul_f32_e32 v206, s16, v187
	v_mul_f32_e32 v207, s16, v188
	v_mul_f32_e32 v208, s16, v189
	v_mul_f32_e32 v209, s16, v190
	v_fma_f32 v142, v187, s16, -v206
	v_fma_f32 v143, v188, s16, -v207
	v_fma_f32 v144, v189, s16, -v208
	v_fma_f32 v145, v190, s16, -v209
	v_fma_f32 v142, v187, s17, v142
; __device__ __forceinline__ float log_sigmoid_(float x) { return fminf(x, 0.f) - log1pf(expf(-fabsf(x))); }
;     __device__ __forceinline__ void operator()(const f32x4 (&acc)[2][2][4][2], const pg8::Unit& u, int wr, int wc, int fr, int fq) const {
;     ...
;                     for (int m = 0; m < 4; ++m) { const int r = row0 + ai * 128 + m * 16; const f32x4 v0 = acc[ai][0][m][0] + b0, v1 = acc[ai][0][m][1] + b1;
;                         f32x4 l0, l1;
; #pragma unroll
;                         for (int j = 0; j < 4; ++j) { l0[j] = log_sigmoid_(v0[j]); l1[j] = log_sigmoid_(v1[j]); }
;                         float* dst = out + (smp ? O_FLS + (size_t)(r - MP) * 8 : O_FLP + (size_t)r * 8);
;                         *(f32x4*)dst = l0; *(f32x4*)(dst + 4) = l1; }
	v_fma_f32 v143, v188, s17, v143
	v_fma_f32 v144, v189, s17, v144
	v_fma_f32 v145, v190, s17, v145
	v_add_f32_e32 v206, v206, v142
	v_add_f32_e32 v207, v207, v143
	v_add_f32_e32 v208, v208, v144
	v_add_f32_e32 v209, v209, v145
	v_mul_f32_e32 v206, v206, v210
	v_mul_f32_e32 v207, v207, v211
	v_mul_f32_e32 v208, v208, v212
	v_mul_f32_e32 v209, v209, v213
	v_min_f32_e32 v187, 0, v177
	v_min_f32_e32 v188, 0, v178
	v_min_f32_e32 v189, 0, v179
	v_min_f32_e32 v190, 0, v182
	v_cmp_eq_f32_e32 vcc, 0, v191
	s_nop 1
	v_cndmask_b32_e32 v206, v206, v183, vcc
	v_cmp_eq_f32_e32 vcc, 0, v0
	s_nop 1
	v_cndmask_b32_e32 v207, v207, v184, vcc
	v_cmp_eq_f32_e32 vcc, 0, v216
	s_nop 1
	v_cndmask_b32_e32 v208, v208, v185, vcc
	v_cmp_eq_f32_e32 vcc, 0, v217
	s_nop 1
	v_cndmask_b32_e32 v209, v209, v186, vcc
	v_sub_f32_e32 v142, v187, v206
	v_sub_f32_e32 v143, v188, v207
	v_sub_f32_e32 v144, v189, v208
	v_sub_f32_e32 v145, v190, v209
	global_store_dwordx4 v[214:215], v[138:141], off
	global_store_dwordx4 v[214:215], v[142:145], off offset:16
	s_nop 1
	v_add_f32_e32 v177, v50, v134
	v_add_f32_e32 v178, v51, v135
	v_add_f32_e32 v179, v52, v136
	v_add_f32_e32 v182, v53, v137
	v_mul_f32_e64 v187, |v177|, s76
	v_mul_f32_e64 v188, |v178|, s76
	v_mul_f32_e64 v189, |v179|, s76
	v_mul_f32_e64 v190, |v182|, s76
	v_fma_f32 v191, |v177|, s76, -v187
	v_fma_f32 v0, |v178|, s76, -v188
	v_fma_f32 v216, |v179|, s76, -v189
	v_fma_f32 v217, |v182|, s76, -v190
	v_rndne_f32_e32 v206, v187
	v_rndne_f32_e32 v207, v188
	v_rndne_f32_e32 v208, v189
	v_rndne_f32_e32 v209, v190
	v_fma_f32 v191, |v177|, s5, v191
	v_fma_f32 v0, |v178|, s5, v0
	v_fma_f32 v216, |v179|, s5, v216
	v_fma_f32 v217, |v182|, s5, v217
	v_sub_f32_e32 v187, v187, v206
	v_sub_f32_e32 v188, v188, v207
	v_sub_f32_e32 v189, v189, v208
	v_sub_f32_e32 v190, v190, v209
	v_add_f32_e32 v187, v187, v191
	v_add_f32_e32 v188, v188, v0
	v_add_f32_e32 v189, v189, v216
	v_add_f32_e32 v190, v190, v217
	v_cvt_i32_f32_e32 v206, v206
	v_cvt_i32_f32_e32 v207, v207
	v_cvt_i32_f32_e32 v208, v208
	v_cvt_i32_f32_e32 v209, v209
	v_exp_f32_e32 v183, v187
	v_exp_f32_e32 v184, v188
	v_exp_f32_e32 v185, v189
	v_exp_f32_e32 v186, v190
	v_ldexp_f32 v183, v183, v206
	v_ldexp_f32 v184, v184, v207
	v_ldexp_f32 v185, v185, v208
	v_ldexp_f32 v186, v186, v209
	v_add_f32_e32 v187, 1.0, v183
	v_add_f32_e32 v188, 1.0, v184
	v_add_f32_e32 v189, 1.0, v185
	v_add_f32_e32 v190, 1.0, v186
	v_add_f32_e32 v191, -1.0, v187
	v_add_f32_e32 v0, -1.0, v188
	v_add_f32_e32 v216, -1.0, v189
	v_add_f32_e32 v217, -1.0, v190
	v_log_f32_e32 v187, v187
	v_log_f32_e32 v188, v188
	v_log_f32_e32 v189, v189
	v_log_f32_e32 v190, v190
	v_rcp_f32_e32 v206, v191
	v_rcp_f32_e32 v207, v0
	v_rcp_f32_e32 v208, v216
	v_rcp_f32_e32 v209, v217
	v_mul_f32_e32 v210, v183, v206
	v_mul_f32_e32 v211, v184, v207
	v_mul_f32_e32 v212, v185, v208
	v_mul_f32_e32 v213, v186, v209
	v_fma_f32 v138, -v210, v191, v183
	v_fma_f32 v139, -v211, v0, v184
	v_fma_f32 v140, -v212, v216, v185
	v_fma_f32 v141, -v213, v217, v186
	v_fma_f32 v210, v138, v206, v210
	v_fma_f32 v211, v139, v207, v211
	v_fma_f32 v212, v140, v208, v212
	v_fma_f32 v213, v141, v209, v213
	v_mul_f32_e32 v206, s16, v187
	v_mul_f32_e32 v207, s16, v188
	v_mul_f32_e32 v208, s16, v189
	v_mul_f32_e32 v209, s16, v190
	v_fma_f32 v138, v187, s16, -v206
	v_fma_f32 v139, v188, s16, -v207
	v_fma_f32 v140, v189, s16, -v208
	v_fma_f32 v141, v190, s16, -v209
	v_fma_f32 v138, v187, s17, v138
	v_fma_f32 v139, v188, s17, v139
	v_fma_f32 v140, v189, s17, v140
	v_fma_f32 v141, v190, s17, v141
	v_add_f32_e32 v206, v206, v138
	v_add_f32_e32 v207, v207, v139
	v_add_f32_e32 v208, v208, v140
	v_add_f32_e32 v209, v209, v141
	v_mul_f32_e32 v206, v206, v210
	v_mul_f32_e32 v207, v207, v211
	v_mul_f32_e32 v208, v208, v212
	v_mul_f32_e32 v209, v209, v213
	v_min_f32_e32 v187, 0, v177
	v_min_f32_e32 v188, 0, v178
	v_min_f32_e32 v189, 0, v179
	v_min_f32_e32 v190, 0, v182
	v_cmp_eq_f32_e32 vcc, 0, v191
	s_nop 1
	v_cndmask_b32_e32 v206, v206, v183, vcc
	v_cmp_eq_f32_e32 vcc, 0, v0
	s_nop 1
	v_cndmask_b32_e32 v207, v207, v184, vcc
	v_cmp_eq_f32_e32 vcc, 0, v216
	s_nop 1
	v_cndmask_b32_e32 v208, v208, v185, vcc
	v_cmp_eq_f32_e32 vcc, 0, v217
	s_nop 1
	v_cndmask_b32_e32 v209, v209, v186, vcc
	v_sub_f32_e32 v138, v187, v206
	v_sub_f32_e32 v139, v188, v207
	v_sub_f32_e32 v140, v189, v208
	v_sub_f32_e32 v141, v190, v209
	v_add_f32_e32 v177, v42, v130
	v_add_f32_e32 v178, v43, v131
	v_add_f32_e32 v179, v44, v132
	v_add_f32_e32 v182, v45, v133
	v_mul_f32_e64 v187, |v177|, s76
	v_mul_f32_e64 v188, |v178|, s76
	v_mul_f32_e64 v189, |v179|, s76
	v_mul_f32_e64 v190, |v182|, s76
	v_fma_f32 v191, |v177|, s76, -v187
	v_fma_f32 v0, |v178|, s76, -v188
	v_fma_f32 v216, |v179|, s76, -v189
	v_fma_f32 v217, |v182|, s76, -v190
	v_rndne_f32_e32 v206, v187
	v_rndne_f32_e32 v207, v188
	v_rndne_f32_e32 v208, v189
	v_rndne_f32_e32 v209, v190
	v_fma_f32 v191, |v177|, s5, v191
	v_fma_f32 v0, |v178|, s5, v0
	v_fma_f32 v216, |v179|, s5, v216
	v_fma_f32 v217, |v182|, s5, v217
	v_sub_f32_e32 v187, v187, v206
	v_sub_f32_e32 v188, v188, v207
	v_sub_f32_e32 v189, v189, v208
	v_sub_f32_e32 v190, v190, v209
	v_add_f32_e32 v187, v187, v191
	v_add_f32_e32 v188, v188, v0
	v_add_f32_e32 v189, v189, v216
	v_add_f32_e32 v190, v190, v217
	v_cvt_i32_f32_e32 v206, v206
	v_cvt_i32_f32_e32 v207, v207
	v_cvt_i32_f32_e32 v208, v208
	v_cvt_i32_f32_e32 v209, v209
	v_exp_f32_e32 v183, v187
	v_exp_f32_e32 v184, v188
	v_exp_f32_e32 v185, v189
	v_exp_f32_e32 v186, v190
	v_ldexp_f32 v183, v183, v206
	v_ldexp_f32 v184, v184, v207
	v_ldexp_f32 v185, v185, v208
	v_ldexp_f32 v186, v186, v209
	v_add_f32_e32 v187, 1.0, v183
	v_add_f32_e32 v188, 1.0, v184
; __device__ __forceinline__ float log_sigmoid_(float x) { return fminf(x, 0.f) - log1pf(expf(-fabsf(x))); }
;     __device__ __forceinline__ void operator()(const f32x4 (&acc)[2][2][4][2], const pg8::Unit& u, int wr, int wc, int fr, int fq) const {
;     ...
;                     for (int m = 0; m < 4; ++m) { const int r = row0 + ai * 128 + m * 16; const f32x4 v0 = acc[ai][0][m][0] + b0, v1 = acc[ai][0][m][1] + b1;
;                         f32x4 l0, l1;
; #pragma unroll
;                         for (int j = 0; j < 4; ++j) { l0[j] = log_sigmoid_(v0[j]); l1[j] = log_sigmoid_(v1[j]); }
;                         float* dst = out + (smp ? O_FLS + (size_t)(r - MP) * 8 : O_FLP + (size_t)r * 8);
;                         *(f32x4*)dst = l0; *(f32x4*)(dst + 4) = l1; }
	v_add_f32_e32 v189, 1.0, v185
	v_add_f32_e32 v190, 1.0, v186
	v_add_f32_e32 v191, -1.0, v187
	v_add_f32_e32 v0, -1.0, v188
	v_add_f32_e32 v216, -1.0, v189
	v_add_f32_e32 v217, -1.0, v190
	v_log_f32_e32 v187, v187
	v_log_f32_e32 v188, v188
	v_log_f32_e32 v189, v189
	v_log_f32_e32 v190, v190
	v_rcp_f32_e32 v206, v191
	v_rcp_f32_e32 v207, v0
	v_rcp_f32_e32 v208, v216
	v_rcp_f32_e32 v209, v217
	v_mul_f32_e32 v210, v183, v206
	v_mul_f32_e32 v211, v184, v207
	v_mul_f32_e32 v212, v185, v208
	v_mul_f32_e32 v213, v186, v209
	v_fma_f32 v142, -v210, v191, v183
	v_fma_f32 v143, -v211, v0, v184
	v_fma_f32 v144, -v212, v216, v185
	v_fma_f32 v145, -v213, v217, v186
	v_fma_f32 v210, v142, v206, v210
	v_fma_f32 v211, v143, v207, v211
	v_fma_f32 v212, v144, v208, v212
	v_fma_f32 v213, v145, v209, v213
	v_mul_f32_e32 v206, s16, v187
	v_mul_f32_e32 v207, s16, v188
	v_mul_f32_e32 v208, s16, v189
	v_mul_f32_e32 v209, s16, v190
	v_fma_f32 v142, v187, s16, -v206
	v_fma_f32 v143, v188, s16, -v207
	v_fma_f32 v144, v189, s16, -v208
	v_fma_f32 v145, v190, s16, -v209
	v_fma_f32 v142, v187, s17, v142
	v_fma_f32 v143, v188, s17, v143
	v_fma_f32 v144, v189, s17, v144
	v_fma_f32 v145, v190, s17, v145
	v_add_f32_e32 v206, v206, v142
	v_add_f32_e32 v207, v207, v143
	v_add_f32_e32 v208, v208, v144
	v_add_f32_e32 v209, v209, v145
	v_mul_f32_e32 v206, v206, v210
	v_mul_f32_e32 v207, v207, v211
	v_mul_f32_e32 v208, v208, v212
	v_mul_f32_e32 v209, v209, v213
	v_min_f32_e32 v187, 0, v177
	v_min_f32_e32 v188, 0, v178
	v_min_f32_e32 v189, 0, v179
	v_min_f32_e32 v190, 0, v182
	v_cmp_eq_f32_e32 vcc, 0, v191
	s_nop 1
	v_cndmask_b32_e32 v206, v206, v183, vcc
	v_cmp_eq_f32_e32 vcc, 0, v0
	s_nop 1
	v_cndmask_b32_e32 v207, v207, v184, vcc
	v_cmp_eq_f32_e32 vcc, 0, v216
	s_nop 1
	v_cndmask_b32_e32 v208, v208, v185, vcc
	v_cmp_eq_f32_e32 vcc, 0, v217
	s_nop 1
	v_cndmask_b32_e32 v209, v209, v186, vcc
	v_sub_f32_e32 v142, v187, v206
	v_sub_f32_e32 v143, v188, v207
	v_sub_f32_e32 v144, v189, v208
	v_sub_f32_e32 v145, v190, v209
	global_store_dwordx4 v[214:215], v[138:141], off offset:512
	global_store_dwordx4 v[214:215], v[142:145], off offset:528
	s_nop 1
	v_add_f32_e32 v177, v34, v134
	v_add_f32_e32 v178, v35, v135
	v_add_f32_e32 v179, v36, v136
	v_add_f32_e32 v182, v37, v137
	v_mul_f32_e64 v187, |v177|, s76
	v_mul_f32_e64 v188, |v178|, s76
	v_mul_f32_e64 v189, |v179|, s76
	v_mul_f32_e64 v190, |v182|, s76
	v_fma_f32 v191, |v177|, s76, -v187
	v_fma_f32 v0, |v178|, s76, -v188
	v_fma_f32 v216, |v179|, s76, -v189
	v_fma_f32 v217, |v182|, s76, -v190
	v_rndne_f32_e32 v206, v187
	v_rndne_f32_e32 v207, v188
	v_rndne_f32_e32 v208, v189
	v_rndne_f32_e32 v209, v190
	v_fma_f32 v191, |v177|, s5, v191
	v_fma_f32 v0, |v178|, s5, v0
	v_fma_f32 v216, |v179|, s5, v216
	v_fma_f32 v217, |v182|, s5, v217
	v_sub_f32_e32 v187, v187, v206
	v_sub_f32_e32 v188, v188, v207
	v_sub_f32_e32 v189, v189, v208
	v_sub_f32_e32 v190, v190, v209
	v_add_f32_e32 v187, v187, v191
	v_add_f32_e32 v188, v188, v0
	v_add_f32_e32 v189, v189, v216
	v_add_f32_e32 v190, v190, v217
	v_cvt_i32_f32_e32 v206, v206
	v_cvt_i32_f32_e32 v207, v207
	v_cvt_i32_f32_e32 v208, v208
	v_cvt_i32_f32_e32 v209, v209
	v_exp_f32_e32 v183, v187
	v_exp_f32_e32 v184, v188
	v_exp_f32_e32 v185, v189
	v_exp_f32_e32 v186, v190
	v_ldexp_f32 v183, v183, v206
	v_ldexp_f32 v184, v184, v207
	v_ldexp_f32 v185, v185, v208
	v_ldexp_f32 v186, v186, v209
	v_add_f32_e32 v187, 1.0, v183
	v_add_f32_e32 v188, 1.0, v184
	v_add_f32_e32 v189, 1.0, v185
	v_add_f32_e32 v190, 1.0, v186
	v_add_f32_e32 v191, -1.0, v187
	v_add_f32_e32 v0, -1.0, v188
	v_add_f32_e32 v216, -1.0, v189
	v_add_f32_e32 v217, -1.0, v190
	v_log_f32_e32 v187, v187
	v_log_f32_e32 v188, v188
	v_log_f32_e32 v189, v189
	v_log_f32_e32 v190, v190
	v_rcp_f32_e32 v206, v191
	v_rcp_f32_e32 v207, v0
	v_rcp_f32_e32 v208, v216
	v_rcp_f32_e32 v209, v217
	v_mul_f32_e32 v210, v183, v206
	v_mul_f32_e32 v211, v184, v207
	v_mul_f32_e32 v212, v185, v208
	v_mul_f32_e32 v213, v186, v209
	v_fma_f32 v138, -v210, v191, v183
	v_fma_f32 v139, -v211, v0, v184
	v_fma_f32 v140, -v212, v216, v185
	v_fma_f32 v141, -v213, v217, v186
	v_fma_f32 v210, v138, v206, v210
	v_fma_f32 v211, v139, v207, v211
	v_fma_f32 v212, v140, v208, v212
	v_fma_f32 v213, v141, v209, v213
	v_mul_f32_e32 v206, s16, v187
	v_mul_f32_e32 v207, s16, v188
	v_mul_f32_e32 v208, s16, v189
	v_mul_f32_e32 v209, s16, v190
	v_fma_f32 v138, v187, s16, -v206
	v_fma_f32 v139, v188, s16, -v207
	v_fma_f32 v140, v189, s16, -v208
	v_fma_f32 v141, v190, s16, -v209
	v_fma_f32 v138, v187, s17, v138
	v_fma_f32 v139, v188, s17, v139
	v_fma_f32 v140, v189, s17, v140
	v_fma_f32 v141, v190, s17, v141
	v_add_f32_e32 v206, v206, v138
	v_add_f32_e32 v207, v207, v139
	v_add_f32_e32 v208, v208, v140
	v_add_f32_e32 v209, v209, v141
	v_mul_f32_e32 v206, v206, v210
	v_mul_f32_e32 v207, v207, v211
	v_mul_f32_e32 v208, v208, v212
	v_mul_f32_e32 v209, v209, v213
	v_min_f32_e32 v187, 0, v177
	v_min_f32_e32 v188, 0, v178
	v_min_f32_e32 v189, 0, v179
	v_min_f32_e32 v190, 0, v182
	v_cmp_eq_f32_e32 vcc, 0, v191
	s_nop 1
	v_cndmask_b32_e32 v206, v206, v183, vcc
	v_cmp_eq_f32_e32 vcc, 0, v0
	s_nop 1
	v_cndmask_b32_e32 v207, v207, v184, vcc
	v_cmp_eq_f32_e32 vcc, 0, v216
	s_nop 1
	v_cndmask_b32_e32 v208, v208, v185, vcc
	v_cmp_eq_f32_e32 vcc, 0, v217
	s_nop 1
	v_cndmask_b32_e32 v209, v209, v186, vcc
	v_sub_f32_e32 v138, v187, v206
	v_sub_f32_e32 v139, v188, v207
	v_sub_f32_e32 v140, v189, v208
	v_sub_f32_e32 v141, v190, v209
	v_add_f32_e32 v177, v26, v130
	v_add_f32_e32 v178, v27, v131
	v_add_f32_e32 v179, v28, v132
	v_add_f32_e32 v182, v29, v133
	v_mul_f32_e64 v187, |v177|, s76
	v_mul_f32_e64 v188, |v178|, s76
; __device__ __forceinline__ float log_sigmoid_(float x) { return fminf(x, 0.f) - log1pf(expf(-fabsf(x))); }
;     __device__ __forceinline__ void operator()(const f32x4 (&acc)[2][2][4][2], const pg8::Unit& u, int wr, int wc, int fr, int fq) const {
;     ...
;                     for (int m = 0; m < 4; ++m) { const int r = row0 + ai * 128 + m * 16; const f32x4 v0 = acc[ai][0][m][0] + b0, v1 = acc[ai][0][m][1] + b1;
;                         f32x4 l0, l1;
; #pragma unroll
;                         for (int j = 0; j < 4; ++j) { l0[j] = log_sigmoid_(v0[j]); l1[j] = log_sigmoid_(v1[j]); }
;                         float* dst = out + (smp ? O_FLS + (size_t)(r - MP) * 8 : O_FLP + (size_t)r * 8);
;                         *(f32x4*)dst = l0; *(f32x4*)(dst + 4) = l1; }
	v_mul_f32_e64 v189, |v179|, s76
	v_mul_f32_e64 v190, |v182|, s76
	v_fma_f32 v191, |v177|, s76, -v187
	v_fma_f32 v0, |v178|, s76, -v188
	v_fma_f32 v216, |v179|, s76, -v189
	v_fma_f32 v217, |v182|, s76, -v190
	v_rndne_f32_e32 v206, v187
	v_rndne_f32_e32 v207, v188
	v_rndne_f32_e32 v208, v189
	v_rndne_f32_e32 v209, v190
	v_fma_f32 v191, |v177|, s5, v191
	v_fma_f32 v0, |v178|, s5, v0
	v_fma_f32 v216, |v179|, s5, v216
	v_fma_f32 v217, |v182|, s5, v217
	v_sub_f32_e32 v187, v187, v206
	v_sub_f32_e32 v188, v188, v207
	v_sub_f32_e32 v189, v189, v208
	v_sub_f32_e32 v190, v190, v209
	v_add_f32_e32 v187, v187, v191
	v_add_f32_e32 v188, v188, v0
	v_add_f32_e32 v189, v189, v216
	v_add_f32_e32 v190, v190, v217
	v_cvt_i32_f32_e32 v206, v206
	v_cvt_i32_f32_e32 v207, v207
	v_cvt_i32_f32_e32 v208, v208
	v_cvt_i32_f32_e32 v209, v209
	v_exp_f32_e32 v183, v187
	v_exp_f32_e32 v184, v188
	v_exp_f32_e32 v185, v189
	v_exp_f32_e32 v186, v190
	v_ldexp_f32 v183, v183, v206
	v_ldexp_f32 v184, v184, v207
	v_ldexp_f32 v185, v185, v208
	v_ldexp_f32 v186, v186, v209
	v_add_f32_e32 v187, 1.0, v183
	v_add_f32_e32 v188, 1.0, v184
	v_add_f32_e32 v189, 1.0, v185
	v_add_f32_e32 v190, 1.0, v186
	v_add_f32_e32 v191, -1.0, v187
	v_add_f32_e32 v0, -1.0, v188
	v_add_f32_e32 v216, -1.0, v189
	v_add_f32_e32 v217, -1.0, v190
	v_log_f32_e32 v187, v187
	v_log_f32_e32 v188, v188
	v_log_f32_e32 v189, v189
	v_log_f32_e32 v190, v190
	v_rcp_f32_e32 v206, v191
	v_rcp_f32_e32 v207, v0
	v_rcp_f32_e32 v208, v216
	v_rcp_f32_e32 v209, v217
	v_mul_f32_e32 v210, v183, v206
	v_mul_f32_e32 v211, v184, v207
	v_mul_f32_e32 v212, v185, v208
	v_mul_f32_e32 v213, v186, v209
	v_fma_f32 v142, -v210, v191, v183
	v_fma_f32 v143, -v211, v0, v184
	v_fma_f32 v144, -v212, v216, v185
	v_fma_f32 v145, -v213, v217, v186
	v_fma_f32 v210, v142, v206, v210
	v_fma_f32 v211, v143, v207, v211
	v_fma_f32 v212, v144, v208, v212
	v_fma_f32 v213, v145, v209, v213
	v_mul_f32_e32 v206, s16, v187
	v_mul_f32_e32 v207, s16, v188
	v_mul_f32_e32 v208, s16, v189
	v_mul_f32_e32 v209, s16, v190
	v_fma_f32 v142, v187, s16, -v206
	v_fma_f32 v143, v188, s16, -v207
	v_fma_f32 v144, v189, s16, -v208
	v_fma_f32 v145, v190, s16, -v209
	v_fma_f32 v142, v187, s17, v142
	v_fma_f32 v143, v188, s17, v143
	v_fma_f32 v144, v189, s17, v144
	v_fma_f32 v145, v190, s17, v145
	v_add_f32_e32 v206, v206, v142
	v_add_f32_e32 v207, v207, v143
	v_add_f32_e32 v208, v208, v144
	v_add_f32_e32 v209, v209, v145
	v_mul_f32_e32 v206, v206, v210
	v_mul_f32_e32 v207, v207, v211
	v_mul_f32_e32 v208, v208, v212
	v_mul_f32_e32 v209, v209, v213
	v_min_f32_e32 v187, 0, v177
	v_min_f32_e32 v188, 0, v178
	v_min_f32_e32 v189, 0, v179
	v_min_f32_e32 v190, 0, v182
	v_cmp_eq_f32_e32 vcc, 0, v191
	s_nop 1
	v_cndmask_b32_e32 v206, v206, v183, vcc
	v_cmp_eq_f32_e32 vcc, 0, v0
	s_nop 1
	v_cndmask_b32_e32 v207, v207, v184, vcc
	v_cmp_eq_f32_e32 vcc, 0, v216
	s_nop 1
	v_cndmask_b32_e32 v208, v208, v185, vcc
	v_cmp_eq_f32_e32 vcc, 0, v217
	s_nop 1
	v_cndmask_b32_e32 v209, v209, v186, vcc
	v_sub_f32_e32 v142, v187, v206
	v_sub_f32_e32 v143, v188, v207
	v_sub_f32_e32 v144, v189, v208
	v_sub_f32_e32 v145, v190, v209
	global_store_dwordx4 v[214:215], v[138:141], off offset:1024
	global_store_dwordx4 v[214:215], v[142:145], off offset:1040
	s_nop 1
	v_add_f32_e32 v177, v18, v134
	v_add_f32_e32 v178, v19, v135
	v_add_f32_e32 v179, v20, v136
	v_add_f32_e32 v182, v21, v137
	v_mul_f32_e64 v187, |v177|, s76
	v_mul_f32_e64 v188, |v178|, s76
	v_mul_f32_e64 v189, |v179|, s76
	v_mul_f32_e64 v190, |v182|, s76
	v_fma_f32 v191, |v177|, s76, -v187
	v_fma_f32 v0, |v178|, s76, -v188
	v_fma_f32 v216, |v179|, s76, -v189
	v_fma_f32 v217, |v182|, s76, -v190
	v_rndne_f32_e32 v206, v187
	v_rndne_f32_e32 v207, v188
	v_rndne_f32_e32 v208, v189
	v_rndne_f32_e32 v209, v190
	v_fma_f32 v191, |v177|, s5, v191
	v_fma_f32 v0, |v178|, s5, v0
	v_fma_f32 v216, |v179|, s5, v216
	v_fma_f32 v217, |v182|, s5, v217
	v_sub_f32_e32 v187, v187, v206
	v_sub_f32_e32 v188, v188, v207
	v_sub_f32_e32 v189, v189, v208
	v_sub_f32_e32 v190, v190, v209
	v_add_f32_e32 v187, v187, v191
	v_add_f32_e32 v188, v188, v0
	v_add_f32_e32 v189, v189, v216
	v_add_f32_e32 v190, v190, v217
	v_cvt_i32_f32_e32 v206, v206
	v_cvt_i32_f32_e32 v207, v207
	v_cvt_i32_f32_e32 v208, v208
	v_cvt_i32_f32_e32 v209, v209
	v_exp_f32_e32 v183, v187
	v_exp_f32_e32 v184, v188
	v_exp_f32_e32 v185, v189
	v_exp_f32_e32 v186, v190
	v_ldexp_f32 v183, v183, v206
	v_ldexp_f32 v184, v184, v207
	v_ldexp_f32 v185, v185, v208
	v_ldexp_f32 v186, v186, v209
	v_add_f32_e32 v187, 1.0, v183
	v_add_f32_e32 v188, 1.0, v184
	v_add_f32_e32 v189, 1.0, v185
	v_add_f32_e32 v190, 1.0, v186
	v_add_f32_e32 v191, -1.0, v187
	v_add_f32_e32 v0, -1.0, v188
	v_add_f32_e32 v216, -1.0, v189
	v_add_f32_e32 v217, -1.0, v190
	v_log_f32_e32 v187, v187
	v_log_f32_e32 v188, v188
	v_log_f32_e32 v189, v189
	v_log_f32_e32 v190, v190
	v_rcp_f32_e32 v206, v191
	v_rcp_f32_e32 v207, v0
	v_rcp_f32_e32 v208, v216
	v_rcp_f32_e32 v209, v217
	v_mul_f32_e32 v210, v183, v206
	v_mul_f32_e32 v211, v184, v207
; __device__ __forceinline__ float log_sigmoid_(float x) { return fminf(x, 0.f) - log1pf(expf(-fabsf(x))); }
;     __device__ __forceinline__ void operator()(const f32x4 (&acc)[2][2][4][2], const pg8::Unit& u, int wr, int wc, int fr, int fq) const {
;     ...
;                     for (int m = 0; m < 4; ++m) { const int r = row0 + ai * 128 + m * 16; const f32x4 v0 = acc[ai][0][m][0] + b0, v1 = acc[ai][0][m][1] + b1;
;                         f32x4 l0, l1;
; #pragma unroll
;                         for (int j = 0; j < 4; ++j) { l0[j] = log_sigmoid_(v0[j]); l1[j] = log_sigmoid_(v1[j]); }
;                         float* dst = out + (smp ? O_FLS + (size_t)(r - MP) * 8 : O_FLP + (size_t)r * 8);
;                         *(f32x4*)dst = l0; *(f32x4*)(dst + 4) = l1; }
	v_mul_f32_e32 v212, v185, v208
	v_mul_f32_e32 v213, v186, v209
	v_fma_f32 v138, -v210, v191, v183
	v_fma_f32 v139, -v211, v0, v184
	v_fma_f32 v140, -v212, v216, v185
	v_fma_f32 v141, -v213, v217, v186
	v_fma_f32 v210, v138, v206, v210
	v_fma_f32 v211, v139, v207, v211
	v_fma_f32 v212, v140, v208, v212
	v_fma_f32 v213, v141, v209, v213
	v_mul_f32_e32 v206, s16, v187
	v_mul_f32_e32 v207, s16, v188
	v_mul_f32_e32 v208, s16, v189
	v_mul_f32_e32 v209, s16, v190
	v_fma_f32 v138, v187, s16, -v206
	v_fma_f32 v139, v188, s16, -v207
	v_fma_f32 v140, v189, s16, -v208
	v_fma_f32 v141, v190, s16, -v209
	v_fma_f32 v138, v187, s17, v138
	v_fma_f32 v139, v188, s17, v139
	v_fma_f32 v140, v189, s17, v140
	v_fma_f32 v141, v190, s17, v141
	v_add_f32_e32 v206, v206, v138
	v_add_f32_e32 v207, v207, v139
	v_add_f32_e32 v208, v208, v140
	v_add_f32_e32 v209, v209, v141
	v_mul_f32_e32 v206, v206, v210
	v_mul_f32_e32 v207, v207, v211
	v_mul_f32_e32 v208, v208, v212
	v_mul_f32_e32 v209, v209, v213
	v_min_f32_e32 v187, 0, v177
	v_min_f32_e32 v188, 0, v178
	v_min_f32_e32 v189, 0, v179
	v_min_f32_e32 v190, 0, v182
	v_cmp_eq_f32_e32 vcc, 0, v191
	s_nop 1
	v_cndmask_b32_e32 v206, v206, v183, vcc
	v_cmp_eq_f32_e32 vcc, 0, v0
	s_nop 1
	v_cndmask_b32_e32 v207, v207, v184, vcc
	v_cmp_eq_f32_e32 vcc, 0, v216
	s_nop 1
	v_cndmask_b32_e32 v208, v208, v185, vcc
	v_cmp_eq_f32_e32 vcc, 0, v217
	s_nop 1
	v_cndmask_b32_e32 v209, v209, v186, vcc
	v_sub_f32_e32 v138, v187, v206
	v_sub_f32_e32 v139, v188, v207
	v_sub_f32_e32 v140, v189, v208
	v_sub_f32_e32 v141, v190, v209
	v_add_f32_e32 v177, v10, v130
	v_add_f32_e32 v178, v11, v131
	v_add_f32_e32 v179, v12, v132
	v_add_f32_e32 v182, v13, v133
	v_mul_f32_e64 v187, |v177|, s76
	v_mul_f32_e64 v188, |v178|, s76
	v_mul_f32_e64 v189, |v179|, s76
	v_mul_f32_e64 v190, |v182|, s76
	v_fma_f32 v191, |v177|, s76, -v187
	v_fma_f32 v0, |v178|, s76, -v188
	v_fma_f32 v216, |v179|, s76, -v189
	v_fma_f32 v217, |v182|, s76, -v190
	v_rndne_f32_e32 v206, v187
	v_rndne_f32_e32 v207, v188
	v_rndne_f32_e32 v208, v189
	v_rndne_f32_e32 v209, v190
	v_fma_f32 v191, |v177|, s5, v191
	v_fma_f32 v0, |v178|, s5, v0
	v_fma_f32 v216, |v179|, s5, v216
	v_fma_f32 v217, |v182|, s5, v217
	v_sub_f32_e32 v187, v187, v206
	v_sub_f32_e32 v188, v188, v207
	v_sub_f32_e32 v189, v189, v208
	v_sub_f32_e32 v190, v190, v209
	v_add_f32_e32 v187, v187, v191
	v_add_f32_e32 v188, v188, v0
	v_add_f32_e32 v189, v189, v216
	v_add_f32_e32 v190, v190, v217
	v_cvt_i32_f32_e32 v206, v206
	v_cvt_i32_f32_e32 v207, v207
	v_cvt_i32_f32_e32 v208, v208
	v_cvt_i32_f32_e32 v209, v209
	v_exp_f32_e32 v183, v187
	v_exp_f32_e32 v184, v188
	v_exp_f32_e32 v185, v189
	v_exp_f32_e32 v186, v190
	v_ldexp_f32 v183, v183, v206
	v_ldexp_f32 v184, v184, v207
	v_ldexp_f32 v185, v185, v208
	v_ldexp_f32 v186, v186, v209
	v_add_f32_e32 v187, 1.0, v183
	v_add_f32_e32 v188, 1.0, v184
	v_add_f32_e32 v189, 1.0, v185
	v_add_f32_e32 v190, 1.0, v186
	v_add_f32_e32 v191, -1.0, v187
	v_add_f32_e32 v0, -1.0, v188
	v_add_f32_e32 v216, -1.0, v189
	v_add_f32_e32 v217, -1.0, v190
	v_log_f32_e32 v187, v187
	v_log_f32_e32 v188, v188
	v_log_f32_e32 v189, v189
	v_log_f32_e32 v190, v190
	v_rcp_f32_e32 v206, v191
	v_rcp_f32_e32 v207, v0
	v_rcp_f32_e32 v208, v216
	v_rcp_f32_e32 v209, v217
	v_mul_f32_e32 v210, v183, v206
	v_mul_f32_e32 v211, v184, v207
	v_mul_f32_e32 v212, v185, v208
	v_mul_f32_e32 v213, v186, v209
	v_fma_f32 v142, -v210, v191, v183
	v_fma_f32 v143, -v211, v0, v184
	v_fma_f32 v144, -v212, v216, v185
	v_fma_f32 v145, -v213, v217, v186
	v_fma_f32 v210, v142, v206, v210
	v_fma_f32 v211, v143, v207, v211
	v_fma_f32 v212, v144, v208, v212
	v_fma_f32 v213, v145, v209, v213
	v_mul_f32_e32 v206, s16, v187
	v_mul_f32_e32 v207, s16, v188
	v_mul_f32_e32 v208, s16, v189
	v_mul_f32_e32 v209, s16, v190
	v_fma_f32 v142, v187, s16, -v206
	v_fma_f32 v143, v188, s16, -v207
	v_fma_f32 v144, v189, s16, -v208
	v_fma_f32 v145, v190, s16, -v209
	v_fma_f32 v142, v187, s17, v142
	v_fma_f32 v143, v188, s17, v143
	v_fma_f32 v144, v189, s17, v144
	v_fma_f32 v145, v190, s17, v145
	v_add_f32_e32 v206, v206, v142
	v_add_f32_e32 v207, v207, v143
	v_add_f32_e32 v208, v208, v144
	v_add_f32_e32 v209, v209, v145
	v_mul_f32_e32 v206, v206, v210
	v_mul_f32_e32 v207, v207, v211
	v_mul_f32_e32 v208, v208, v212
	v_mul_f32_e32 v209, v209, v213
	v_min_f32_e32 v187, 0, v177
	v_min_f32_e32 v188, 0, v178
	v_min_f32_e32 v189, 0, v179
	v_min_f32_e32 v190, 0, v182
	v_cmp_eq_f32_e32 vcc, 0, v191
	s_nop 1
	v_cndmask_b32_e32 v206, v206, v183, vcc
	v_cmp_eq_f32_e32 vcc, 0, v0
	s_nop 1
	v_cndmask_b32_e32 v207, v207, v184, vcc
	v_cmp_eq_f32_e32 vcc, 0, v216
	s_nop 1
	v_cndmask_b32_e32 v208, v208, v185, vcc
	v_cmp_eq_f32_e32 vcc, 0, v217
	s_nop 1
	v_cndmask_b32_e32 v209, v209, v186, vcc
	v_sub_f32_e32 v142, v187, v206
	v_sub_f32_e32 v143, v188, v207
	v_sub_f32_e32 v144, v189, v208
	v_sub_f32_e32 v145, v190, v209
	global_store_dwordx4 v[214:215], v[138:141], off offset:1536
	global_store_dwordx4 v[214:215], v[142:145], off offset:1552
	s_nop 1
